# P0 unit list rebalanced: the 192 workgroups with an adaLN unit take 3 weight-transpose units each, the other 64 take 5 (was 3-4 vs 4-5), on top of v14b
# baseline (speedup 1.0000x reference)
; DI void phase0(const Params& p, unsigned char* ws, unsigned char* ldsb, int tid) {
;     ...
;     for (int u = blockIdx.x; u < NU; u += gridDim.x) {
;         int r = u;
;         if (r < U_ADA) { p0_ada_unit(p, ws, r, lds, tid); continue; } r -= U_ADA;
;         if (r < U_ROPE) {
;             const int e = r * 512 + tid;
;             if (e < 2048) { const int pos = e >> 4, j = e & 15; const float inv = powf(10000.f, -(float)j / 16.f); const float a = (float)pos * inv;
;                 ((f32x2*)(ws + WS_ROPEA))[e] = (f32x2){cosf(a), sinf(a)}; }
;             else { const int e2 = e - 2048; const int pos = e2 >> 3, j = e2 & 7; const float inv = powf(10000.f, -(float)j / 8.f); const float a = (float)pos * inv;
;                 ((f32x2*)(ws + WS_ROPEB))[e2] = (f32x2){cosf(a), sinf(a)}; }
;             continue;
;         } r -= U_ROPE;
;         if (r < U_IN0) { p0_transpose_unit(p.in[7], 1024, 2560, 2560, (bf16_t*)(ws + WS_WT_IN0), r, lds, tid); continue; } r -= U_IN0;
;         p0_transpose_unit(p.in[9], 1024, 1024, 1024, (bf16_t*)(ws + WS_WT_O0), r, lds, tid);
;     }
.LBB0_28:
	s_or_b64 exec, exec, s[8:9]
	s_andn2_b64 vcc, exec, s[74:75]
	s_cbranch_vccnz .LBB0_22
	s_mov_b32 s69, s2
	s_load_dword s8, s[72:73], 0x0
	s_waitcnt lgkmcnt(0)
	s_cmp_lg_u32 s8, 0x100
	s_cbranch_scc1 .Lp0s_done
	s_cmp_lt_u32 s2, 198
	s_cbranch_scc1 .Lp0s_done
	s_add_i32 s69, s2, 582
.Lp0s_done:
	s_branch .LBB0_32
.LBB0_30:
	s_or_b64 exec, exec, s[12:13]
	s_waitcnt lgkmcnt(0)
	s_barrier
.LBB0_31:
	s_load_dword s8, s[72:73], 0x0
	s_waitcnt lgkmcnt(0)
	s_cmp_lg_u32 s8, 0x100
	s_cbranch_scc1 .Lp0a_orig
	s_cmp_lt_u32 s2, 192
	s_cbranch_scc0 .Lp0a_B
	s_cmp_lt_u32 s69, 192
	s_cselect_b32 s8, 6, 0
	s_add_i32 s69, s69, s8
	s_addk_i32 s69, 0xc0
	s_cmp_lt_u32 s69, 774
	s_branch .Lp0a_end
.Lp0a_B:
	s_cmp_lt_u32 s69, 198
	s_cbranch_scc0 .Lp0a_B2
	s_add_i32 s69, s2, 582
	s_branch .Lp0a_B3
.Lp0a_B2:
	s_add_i32 s69, s69, 64
.Lp0a_B3:
	s_cmp_lt_u32 s69, 0x446
	s_branch .Lp0a_end
.Lp0a_orig:
	s_add_i32 s69, s69, s8
	s_cmpk_lt_i32 s69, 0x446
.Lp0a_end:
	s_cbranch_scc0 .LBB0_22
